# input GEMM K-loop: LDS-DMA loads use scalar base + 32-bit lane offset (address arithmetic on SALU), LDS read bases formed once per tile: 20 fewer VALU per two K-tiles; on top of LDS-staged attention f
# baseline (speedup 1.0000x reference)
; template <class Epi, class Sched, bool ALIGN_EPI = false, bool SP2 = false>
; __device__ __forceinline__ void gemm_phase(PG8_LAS unsigned char* lds, const Gemm g, const Sched& S, const Epi& E, const int tid_in) {
;     ...
;     const int aoff = lds_byte(wr * 64 + fr, fq * 8), boff = lds_byte(wc * 32 + fr, fq * 8);
;     ...
;     f32x4 acc[2][2][4][2];
; #pragma unroll
;     for (int a = 0; a < 2; ++a)
; #pragma unroll
;         for (int b = 0; b < 2; ++b)
; #pragma unroll
;             for (int m = 0; m < 4; ++m)
; #pragma unroll
;                 for (int n = 0; n < 2; ++n) acc[a][b][m][n] = (f32x4){0.f, 0.f, 0.f, 0.f};
.LBB0_235:
	v_mov_b32_e32 v127, 0
	s_andn2_b64 vcc, exec, s[14:15]
	v_mov_b32_e32 v126, v127
	v_mov_b32_e32 v125, v127
	v_mov_b32_e32 v124, v127
	v_mov_b32_e32 v123, v127
	v_mov_b32_e32 v122, v127
	v_mov_b32_e32 v121, v127
	v_mov_b32_e32 v120, v127
	v_mov_b32_e32 v111, v127
	v_mov_b32_e32 v110, v127
	v_mov_b32_e32 v109, v127
	v_mov_b32_e32 v108, v127
	v_mov_b32_e32 v107, v127
	v_mov_b32_e32 v106, v127
	v_mov_b32_e32 v105, v127
	v_mov_b32_e32 v104, v127
	v_mov_b32_e32 v95, v127
	v_mov_b32_e32 v94, v127
	v_mov_b32_e32 v93, v127
	v_mov_b32_e32 v92, v127
	v_mov_b32_e32 v91, v127
	v_mov_b32_e32 v90, v127
	v_mov_b32_e32 v89, v127
	v_mov_b32_e32 v88, v127
	v_mov_b32_e32 v79, v127
	v_mov_b32_e32 v78, v127
	v_mov_b32_e32 v77, v127
	v_mov_b32_e32 v76, v127
	v_mov_b32_e32 v75, v127
	v_mov_b32_e32 v74, v127
	v_mov_b32_e32 v73, v127
	v_mov_b32_e32 v72, v127
	v_mov_b32_e32 v119, v127
	v_mov_b32_e32 v118, v127
	v_mov_b32_e32 v117, v127
	v_mov_b32_e32 v116, v127
	v_mov_b32_e32 v115, v127
	v_mov_b32_e32 v114, v127
	v_mov_b32_e32 v113, v127
	v_mov_b32_e32 v112, v127
	v_mov_b32_e32 v103, v127
	v_mov_b32_e32 v102, v127
	v_mov_b32_e32 v101, v127
	v_mov_b32_e32 v100, v127
	v_mov_b32_e32 v99, v127
	v_mov_b32_e32 v98, v127
	v_mov_b32_e32 v97, v127
	v_mov_b32_e32 v96, v127
	v_mov_b32_e32 v87, v127
	v_mov_b32_e32 v86, v127
	v_mov_b32_e32 v85, v127
	v_mov_b32_e32 v84, v127
	v_mov_b32_e32 v83, v127
	v_mov_b32_e32 v82, v127
	v_mov_b32_e32 v81, v127
	v_mov_b32_e32 v80, v127
	v_mov_b32_e32 v71, v127
	v_mov_b32_e32 v70, v127
	v_mov_b32_e32 v69, v127
	v_mov_b32_e32 v68, v127
	v_mov_b32_e32 v67, v127
	v_mov_b32_e32 v66, v127
	v_mov_b32_e32 v65, v127
	v_mov_b32_e32 v64, v127
	v_mov_b32_e32 v63, v127
	v_mov_b32_e32 v62, v127
	v_mov_b32_e32 v61, v127
	v_mov_b32_e32 v60, v127
	v_mov_b32_e32 v59, v127
	v_mov_b32_e32 v58, v127
	v_mov_b32_e32 v57, v127
	v_mov_b32_e32 v56, v127
	v_mov_b32_e32 v47, v127
	v_mov_b32_e32 v46, v127
	v_mov_b32_e32 v45, v127
	v_mov_b32_e32 v44, v127
	v_mov_b32_e32 v43, v127
	v_mov_b32_e32 v42, v127
	v_mov_b32_e32 v41, v127
	v_mov_b32_e32 v40, v127
	v_mov_b32_e32 v31, v127
	v_mov_b32_e32 v30, v127
	v_mov_b32_e32 v29, v127
	v_mov_b32_e32 v28, v127
	v_mov_b32_e32 v27, v127
	v_mov_b32_e32 v26, v127
	v_mov_b32_e32 v25, v127
	v_mov_b32_e32 v24, v127
	v_mov_b32_e32 v15, v127
	v_mov_b32_e32 v14, v127
	v_mov_b32_e32 v13, v127
	v_mov_b32_e32 v12, v127
	v_mov_b32_e32 v11, v127
	v_mov_b32_e32 v10, v127
	v_mov_b32_e32 v9, v127
	v_mov_b32_e32 v8, v127
	v_mov_b32_e32 v55, v127
	v_mov_b32_e32 v54, v127
	v_mov_b32_e32 v53, v127
	v_mov_b32_e32 v52, v127
	v_mov_b32_e32 v51, v127
	v_mov_b32_e32 v50, v127
	v_mov_b32_e32 v49, v127
	v_mov_b32_e32 v48, v127
	v_mov_b32_e32 v39, v127
	v_mov_b32_e32 v38, v127
	v_mov_b32_e32 v37, v127
	v_mov_b32_e32 v36, v127
	v_mov_b32_e32 v35, v127
	v_mov_b32_e32 v34, v127
	v_mov_b32_e32 v33, v127
	v_mov_b32_e32 v32, v127
	v_mov_b32_e32 v23, v127
	v_mov_b32_e32 v22, v127
	v_mov_b32_e32 v21, v127
	v_mov_b32_e32 v20, v127
	v_mov_b32_e32 v19, v127
	v_mov_b32_e32 v18, v127
	v_mov_b32_e32 v17, v127
	v_mov_b32_e32 v16, v127
	v_mov_b32_e32 v7, v127
	v_mov_b32_e32 v6, v127
	v_mov_b32_e32 v5, v127
	v_mov_b32_e32 v4, v127
	v_mov_b32_e32 v3, v127
	v_mov_b32_e32 v2, v127
	v_mov_b32_e32 v1, v127
	v_mov_b32_e32 v0, v127
	s_cbranch_vccnz .LBB0_239
	s_add_u32 s20, s20, 0x80
	s_addc_u32 s21, s21, 0
	s_add_u32 s49, s22, 0x100
	v_mov_b32_e32 v0, 0
	s_addc_u32 s50, s23, 0
	s_mov_b32 s22, 0
	v_mov_b32_e32 v1, v0
	v_mov_b32_e32 v2, v0
	v_mov_b32_e32 v3, v0
	v_mov_b32_e32 v4, v0
	v_mov_b32_e32 v5, v0
	v_mov_b32_e32 v6, v0
	v_mov_b32_e32 v7, v0
	v_mov_b32_e32 v16, v0
	v_mov_b32_e32 v17, v0
	v_mov_b32_e32 v18, v0
	v_mov_b32_e32 v19, v0
	v_mov_b32_e32 v20, v0
	v_mov_b32_e32 v21, v0
	v_mov_b32_e32 v22, v0
	v_mov_b32_e32 v23, v0
	v_mov_b32_e32 v32, v0
	v_mov_b32_e32 v33, v0
	v_mov_b32_e32 v34, v0
	v_mov_b32_e32 v35, v0
	v_mov_b32_e32 v36, v0
	v_mov_b32_e32 v37, v0
	v_mov_b32_e32 v38, v0
	v_mov_b32_e32 v39, v0
	v_mov_b32_e32 v48, v0
	v_mov_b32_e32 v49, v0
	v_mov_b32_e32 v50, v0
	v_mov_b32_e32 v51, v0
	v_mov_b32_e32 v52, v0
	v_mov_b32_e32 v53, v0
	v_mov_b32_e32 v54, v0
	v_mov_b32_e32 v55, v0
	v_mov_b32_e32 v8, v0
	v_mov_b32_e32 v9, v0
	v_mov_b32_e32 v10, v0
	v_mov_b32_e32 v11, v0
	v_mov_b32_e32 v12, v0
	v_mov_b32_e32 v13, v0
	v_mov_b32_e32 v14, v0
	v_mov_b32_e32 v15, v0
	v_mov_b32_e32 v24, v0
	v_mov_b32_e32 v25, v0
	v_mov_b32_e32 v26, v0
	v_mov_b32_e32 v27, v0
	v_mov_b32_e32 v28, v0
	v_mov_b32_e32 v29, v0
	v_mov_b32_e32 v30, v0
	v_mov_b32_e32 v31, v0
	v_mov_b32_e32 v40, v0
	v_mov_b32_e32 v41, v0
	v_mov_b32_e32 v42, v0
	v_mov_b32_e32 v43, v0
	v_mov_b32_e32 v44, v0
	v_mov_b32_e32 v45, v0
	v_mov_b32_e32 v46, v0
	v_mov_b32_e32 v47, v0
	v_mov_b32_e32 v56, v0
	v_mov_b32_e32 v57, v0
	v_mov_b32_e32 v58, v0
	v_mov_b32_e32 v59, v0
	v_mov_b32_e32 v60, v0
	v_mov_b32_e32 v61, v0
	v_mov_b32_e32 v62, v0
	v_mov_b32_e32 v63, v0
	v_mov_b32_e32 v64, v0
	v_mov_b32_e32 v65, v0
	v_mov_b32_e32 v66, v0
	v_mov_b32_e32 v67, v0
	v_mov_b32_e32 v68, v0
	v_mov_b32_e32 v69, v0
	v_mov_b32_e32 v70, v0
	v_mov_b32_e32 v71, v0
	v_mov_b32_e32 v80, v0
	v_mov_b32_e32 v81, v0
	v_mov_b32_e32 v82, v0
	v_mov_b32_e32 v83, v0
	v_mov_b32_e32 v84, v0
	v_mov_b32_e32 v85, v0
	v_mov_b32_e32 v86, v0
	v_mov_b32_e32 v87, v0
	v_mov_b32_e32 v96, v0
	v_mov_b32_e32 v97, v0
	v_mov_b32_e32 v98, v0
	v_mov_b32_e32 v99, v0
	v_mov_b32_e32 v100, v0
	v_mov_b32_e32 v101, v0
	v_mov_b32_e32 v102, v0
	v_mov_b32_e32 v103, v0
	v_mov_b32_e32 v112, v0
	v_mov_b32_e32 v113, v0
	v_mov_b32_e32 v114, v0
	v_mov_b32_e32 v115, v0
	v_mov_b32_e32 v116, v0
	v_mov_b32_e32 v117, v0
	v_mov_b32_e32 v118, v0
	v_mov_b32_e32 v119, v0
	v_mov_b32_e32 v72, v0
	v_mov_b32_e32 v73, v0
	v_mov_b32_e32 v74, v0
	v_mov_b32_e32 v75, v0
	v_mov_b32_e32 v76, v0
	v_mov_b32_e32 v77, v0
	v_mov_b32_e32 v78, v0
	v_mov_b32_e32 v79, v0
	v_mov_b32_e32 v88, v0
	v_mov_b32_e32 v89, v0
	v_mov_b32_e32 v90, v0
	v_mov_b32_e32 v91, v0
	v_mov_b32_e32 v92, v0
	v_mov_b32_e32 v93, v0
	v_mov_b32_e32 v94, v0
	v_mov_b32_e32 v95, v0
	v_mov_b32_e32 v104, v0
	v_mov_b32_e32 v105, v0
	v_mov_b32_e32 v106, v0
	v_mov_b32_e32 v107, v0
	v_mov_b32_e32 v108, v0
	v_mov_b32_e32 v109, v0
	v_mov_b32_e32 v110, v0
	v_mov_b32_e32 v111, v0
	v_mov_b32_e32 v120, v0
	v_mov_b32_e32 v121, v0
	v_mov_b32_e32 v122, v0
	v_mov_b32_e32 v123, v0
	v_mov_b32_e32 v124, v0
	v_mov_b32_e32 v125, v0
	v_mov_b32_e32 v126, v0
	v_mov_b32_e32 v127, v0
	v_add_u32_e32 v242, 0x10000, v146
	v_add_u32_e32 v243, 0x14000, v146
	v_add_u32_e32 v244, 0x18000, v146
	v_add_u32_e32 v245, 0x1c000, v146
; #define PG8_STAGE(bufoff, gbase, voff) do { _Pragma("unroll") for (int _i = 0; _i < 2; ++_i) \
;         __builtin_amdgcn_global_load_lds((const unsigned*)((const char*)(gbase) + (voff)[_i]), (PG8_LAS unsigned*)(lds + (bufoff) + ldsw + _i * 8192), 16, 0, 0); } while (0)
; #define PG8_LDA(dst, b, h) do { _Pragma("unroll") for (int m = 0; m < 4; ++m) _Pragma("unroll") for (int k = 0; k < 2; ++k) dst[m][k] = *(const PG8_LAS bf16x8*)(lds + PG8_SA(b, h) + aoff + m * 2048 + k * 1024); } while (0)
; #define PG8_LDB(dst, b, h) do { _Pragma("unroll") for (int n = 0; n < 2; ++n) _Pragma("unroll") for (int k = 0; k < 2; ++k) dst[n][k] = *(const PG8_LAS bf16x8*)(lds + PG8_SB(b, h) + boff + n * 2048 + k * 1024); } while (0)
; #define PG8_MMA(ai, bj, At, Bt) do { __builtin_amdgcn_s_setprio(1); _Pragma("unroll") for (int m = 0; m < 4; ++m) _Pragma("unroll") for (int n = 0; n < 2; ++n) _Pragma("unroll") for (int k = 0; k < 2; ++k) \
;         acc[ai][bj][m][n] = __builtin_amdgcn_mfma_f32_16x16x32_bf16(Bt[n][k], At[m][k], acc[ai][bj][m][n], 0, 0, 0); __builtin_amdgcn_s_setprio(0); } while (0)
; #define PG8_WAIT_V(n) asm volatile("s_waitcnt vmcnt(" #n ")" ::: "memory")
; #define PG8_WAIT_L(n) asm volatile("s_waitcnt lgkmcnt(" #n ")" ::: "memory")
; #define PG8_BAR __builtin_amdgcn_s_barrier()
; #define PG8_SCHED __builtin_amdgcn_sched_barrier(0)
; template <class Epi, class Sched, bool ALIGN_EPI = false, bool SP2 = false>
; __device__ __forceinline__ void gemm_phase(PG8_LAS unsigned char* lds, const Gemm g, const Sched& S, const Epi& E, const int tid_in) {
;     ...
;             PG8_LDB(B0, 0, 0); PG8_LDB(B1, 0, 1); PG8_SCHED; PG8_LDA(At, 0, 0); PG8_STAGE(PG8_SA(1, 1), a1 + hstep, voffA);
;             PG8_WAIT_V(8); PG8_WAIT_L(0); PG8_BAR; PG8_MMA(0, 0, At, B0); PG8_MMA(0, 1, At, B1); PG8_BAR; PG8_SCHED;
;             PG8_LDA(At, 0, 1); PG8_STAGE(PG8_SB(0, 0), b2, voffB); PG8_STAGE(PG8_SB(0, 1), b2 + hstep, voffB); PG8_STAGE(PG8_SA(0, 0), a2, voffA);
;             PG8_WAIT_V(8); PG8_WAIT_L(0); PG8_BAR; PG8_MMA(1, 0, At, B0); PG8_MMA(1, 1, At, B1); PG8_BAR; PG8_SCHED;
.LBB0_237:
	s_add_i32 s51, s22, 2
	s_add_u32 s54, s20, 0x80
	s_addc_u32 s23, s21, 0
	s_add_i32 s56, 0, 0x10000
	s_cmp_eq_u32 s40, s22
	s_cselect_b32 s23, s3, s23
	s_cselect_b32 s22, s2, s54
	s_cselect_b32 s55, s19, s50
	s_cselect_b32 s54, s18, s49
	s_add_i32 s57, 0, 0x14000
	ds_read_b128 v[142:145], v242
	ds_read_b128 v[148:151], v242 offset:1024
	ds_read_b128 v[152:155], v242 offset:2048
	ds_read_b128 v[156:159], v242 offset:3072
	ds_read_b128 v[160:163], v243
	ds_read_b128 v[164:167], v243 offset:1024
	ds_read_b128 v[168:171], v243 offset:2048
	ds_read_b128 v[172:175], v243 offset:3072
	s_add_i32 m0, s31, 0xc000
	ds_read_b128 v[176:179], v147
	ds_read_b128 v[180:183], v147 offset:1024
	ds_read_b128 v[190:193], v147 offset:2048
	ds_read_b128 v[196:199], v147 offset:3072
	ds_read_b128 v[200:203], v147 offset:4096
	ds_read_b128 v[212:215], v147 offset:5120
	ds_read_b128 v[216:219], v147 offset:6144
	ds_read_b128 v[220:223], v147 offset:7168
	global_load_lds_dwordx4 v138, s[20:21]
	s_add_i32 m0, s31, 0xe000
	s_nop 0
	global_load_lds_dwordx4 v140, s[20:21]
	s_waitcnt vmcnt(8)
	s_waitcnt lgkmcnt(0)
	s_barrier
	s_setprio 1
	s_waitcnt lgkmcnt(0)
	v_mfma_f32_16x16x32_bf16 v[124:127], v[142:145], v[176:179], v[124:127]
	v_mfma_f32_16x16x32_bf16 v[120:123], v[152:155], v[176:179], v[120:123]
	v_mfma_f32_16x16x32_bf16 v[108:111], v[142:145], v[190:193], v[108:111]
	v_mfma_f32_16x16x32_bf16 v[104:107], v[152:155], v[190:193], v[104:107]
	v_mfma_f32_16x16x32_bf16 v[92:95], v[142:145], v[200:203], v[92:95]
	v_mfma_f32_16x16x32_bf16 v[88:91], v[152:155], v[200:203], v[88:91]
	v_mfma_f32_16x16x32_bf16 v[76:79], v[142:145], v[216:219], v[76:79]
	v_mfma_f32_16x16x32_bf16 v[72:75], v[152:155], v[216:219], v[72:75]
	v_mfma_f32_16x16x32_bf16 v[124:127], v[148:151], v[180:183], v[124:127]
	v_mfma_f32_16x16x32_bf16 v[120:123], v[156:159], v[180:183], v[120:123]
	v_mfma_f32_16x16x32_bf16 v[108:111], v[148:151], v[196:199], v[108:111]
	v_mfma_f32_16x16x32_bf16 v[104:107], v[156:159], v[196:199], v[104:107]
	v_mfma_f32_16x16x32_bf16 v[92:95], v[148:151], v[212:215], v[92:95]
	v_mfma_f32_16x16x32_bf16 v[88:91], v[156:159], v[212:215], v[88:91]
	v_mfma_f32_16x16x32_bf16 v[76:79], v[148:151], v[220:223], v[76:79]
	v_mfma_f32_16x16x32_bf16 v[72:75], v[156:159], v[220:223], v[72:75]
	s_setprio 0
	s_setprio 1
	v_mfma_f32_16x16x32_bf16 v[116:119], v[160:163], v[176:179], v[116:119]
	v_mfma_f32_16x16x32_bf16 v[112:115], v[168:171], v[176:179], v[112:115]
	v_mfma_f32_16x16x32_bf16 v[100:103], v[160:163], v[190:193], v[100:103]
	v_mfma_f32_16x16x32_bf16 v[96:99], v[168:171], v[190:193], v[96:99]
	v_mfma_f32_16x16x32_bf16 v[84:87], v[160:163], v[200:203], v[84:87]
	v_mfma_f32_16x16x32_bf16 v[80:83], v[168:171], v[200:203], v[80:83]
	v_mfma_f32_16x16x32_bf16 v[68:71], v[160:163], v[216:219], v[68:71]
	v_mfma_f32_16x16x32_bf16 v[64:67], v[168:171], v[216:219], v[64:67]
	v_mfma_f32_16x16x32_bf16 v[116:119], v[164:167], v[180:183], v[116:119]
	v_mfma_f32_16x16x32_bf16 v[112:115], v[172:175], v[180:183], v[112:115]
	v_mfma_f32_16x16x32_bf16 v[100:103], v[164:167], v[196:199], v[100:103]
	v_mfma_f32_16x16x32_bf16 v[96:99], v[172:175], v[196:199], v[96:99]
	v_mfma_f32_16x16x32_bf16 v[84:87], v[164:167], v[212:215], v[84:87]
	v_mfma_f32_16x16x32_bf16 v[80:83], v[172:175], v[212:215], v[80:83]
	v_mfma_f32_16x16x32_bf16 v[68:71], v[164:167], v[220:223], v[68:71]
	v_mfma_f32_16x16x32_bf16 v[64:67], v[172:175], v[220:223], v[64:67]
	s_setprio 0
	s_barrier
	s_add_i32 s56, s56, s30
	s_mov_b32 m0, s56
	ds_read_b128 v[176:179], v147 offset:16384
	ds_read_b128 v[180:183], v147 offset:17408
	ds_read_b128 v[190:193], v147 offset:18432
	ds_read_b128 v[196:199], v147 offset:19456
	ds_read_b128 v[200:203], v147 offset:20480
	ds_read_b128 v[212:215], v147 offset:21504
	ds_read_b128 v[216:219], v147 offset:22528
	ds_read_b128 v[220:223], v147 offset:23552
	global_load_lds_dwordx4 v130, s[54:55]
	s_add_i32 m0, s56, 0x2000
	s_add_i32 s56, s57, s30
	global_load_lds_dwordx4 v134, s[54:55]
	s_add_u32 s54, s54, s4
	s_addc_u32 s55, s55, s5
	s_mov_b32 m0, s56
	s_nop 0
	global_load_lds_dwordx4 v130, s[54:55]
	s_add_i32 m0, s56, 0x2000
	s_nop 0
	global_load_lds_dwordx4 v134, s[54:55]
	s_mov_b32 m0, s31
	s_nop 0
	global_load_lds_dwordx4 v128, s[22:23]
	s_mov_b32 m0, s34
	s_nop 0
	global_load_lds_dwordx4 v132, s[22:23]
	s_waitcnt vmcnt(8)
	s_waitcnt lgkmcnt(0)
	s_barrier
	s_setprio 1
	s_waitcnt lgkmcnt(0)
	v_mfma_f32_16x16x32_bf16 v[60:63], v[142:145], v[176:179], v[60:63]
	v_mfma_f32_16x16x32_bf16 v[56:59], v[152:155], v[176:179], v[56:59]
	v_mfma_f32_16x16x32_bf16 v[44:47], v[142:145], v[190:193], v[44:47]
	v_mfma_f32_16x16x32_bf16 v[40:43], v[152:155], v[190:193], v[40:43]
	v_mfma_f32_16x16x32_bf16 v[28:31], v[142:145], v[200:203], v[28:31]
	v_mfma_f32_16x16x32_bf16 v[24:27], v[152:155], v[200:203], v[24:27]
	v_mfma_f32_16x16x32_bf16 v[12:15], v[142:145], v[216:219], v[12:15]
	v_mfma_f32_16x16x32_bf16 v[8:11], v[152:155], v[216:219], v[8:11]
	v_mfma_f32_16x16x32_bf16 v[60:63], v[148:151], v[180:183], v[60:63]
	v_mfma_f32_16x16x32_bf16 v[56:59], v[156:159], v[180:183], v[56:59]
	v_mfma_f32_16x16x32_bf16 v[44:47], v[148:151], v[196:199], v[44:47]
	v_mfma_f32_16x16x32_bf16 v[40:43], v[156:159], v[196:199], v[40:43]
	v_mfma_f32_16x16x32_bf16 v[28:31], v[148:151], v[212:215], v[28:31]
	v_mfma_f32_16x16x32_bf16 v[24:27], v[156:159], v[212:215], v[24:27]
	v_mfma_f32_16x16x32_bf16 v[12:15], v[148:151], v[220:223], v[12:15]
	v_mfma_f32_16x16x32_bf16 v[8:11], v[156:159], v[220:223], v[8:11]
	s_setprio 0
	s_setprio 1
	v_mfma_f32_16x16x32_bf16 v[52:55], v[160:163], v[176:179], v[52:55]
	v_mfma_f32_16x16x32_bf16 v[48:51], v[168:171], v[176:179], v[48:51]
	v_mfma_f32_16x16x32_bf16 v[36:39], v[160:163], v[190:193], v[36:39]
	v_mfma_f32_16x16x32_bf16 v[32:35], v[168:171], v[190:193], v[32:35]
	v_mfma_f32_16x16x32_bf16 v[20:23], v[160:163], v[200:203], v[20:23]
	v_mfma_f32_16x16x32_bf16 v[16:19], v[168:171], v[200:203], v[16:19]
	v_mfma_f32_16x16x32_bf16 v[4:7], v[160:163], v[216:219], v[4:7]
	v_mfma_f32_16x16x32_bf16 v[0:3], v[168:171], v[216:219], v[0:3]
	v_mfma_f32_16x16x32_bf16 v[52:55], v[164:167], v[180:183], v[52:55]
	v_mfma_f32_16x16x32_bf16 v[48:51], v[172:175], v[180:183], v[48:51]
	v_mfma_f32_16x16x32_bf16 v[36:39], v[164:167], v[196:199], v[36:39]
	v_mfma_f32_16x16x32_bf16 v[32:35], v[172:175], v[196:199], v[32:35]
	v_mfma_f32_16x16x32_bf16 v[20:23], v[164:167], v[212:215], v[20:23]
	v_mfma_f32_16x16x32_bf16 v[16:19], v[172:175], v[212:215], v[16:19]
	v_mfma_f32_16x16x32_bf16 v[4:7], v[164:167], v[220:223], v[4:7]
	v_mfma_f32_16x16x32_bf16 v[0:3], v[172:175], v[220:223], v[0:3]
	s_setprio 0
	s_barrier
; #define PG8_STAGE(bufoff, gbase, voff) do { _Pragma("unroll") for (int _i = 0; _i < 2; ++_i) \
;         __builtin_amdgcn_global_load_lds((const unsigned*)((const char*)(gbase) + (voff)[_i]), (PG8_LAS unsigned*)(lds + (bufoff) + ldsw + _i * 8192), 16, 0, 0); } while (0)
; #define PG8_LDA(dst, b, h) do { _Pragma("unroll") for (int m = 0; m < 4; ++m) _Pragma("unroll") for (int k = 0; k < 2; ++k) dst[m][k] = *(const PG8_LAS bf16x8*)(lds + PG8_SA(b, h) + aoff + m * 2048 + k * 1024); } while (0)
; #define PG8_LDB(dst, b, h) do { _Pragma("unroll") for (int n = 0; n < 2; ++n) _Pragma("unroll") for (int k = 0; k < 2; ++k) dst[n][k] = *(const PG8_LAS bf16x8*)(lds + PG8_SB(b, h) + boff + n * 2048 + k * 1024); } while (0)
; #define PG8_MMA(ai, bj, At, Bt) do { __builtin_amdgcn_s_setprio(1); _Pragma("unroll") for (int m = 0; m < 4; ++m) _Pragma("unroll") for (int n = 0; n < 2; ++n) _Pragma("unroll") for (int k = 0; k < 2; ++k) \
;         acc[ai][bj][m][n] = __builtin_amdgcn_mfma_f32_16x16x32_bf16(Bt[n][k], At[m][k], acc[ai][bj][m][n], 0, 0, 0); __builtin_amdgcn_s_setprio(0); } while (0)
; #define PG8_WAIT_V(n) asm volatile("s_waitcnt vmcnt(" #n ")" ::: "memory")
; #define PG8_WAIT_L(n) asm volatile("s_waitcnt lgkmcnt(" #n ")" ::: "memory")
; #define PG8_BAR __builtin_amdgcn_s_barrier()
; #define PG8_SCHED __builtin_amdgcn_sched_barrier(0)
; template <class Epi, class Sched, bool ALIGN_EPI = false, bool SP2 = false>
; __device__ __forceinline__ void gemm_phase(PG8_LAS unsigned char* lds, const Gemm g, const Sched& S, const Epi& E, const int tid_in) {
;     ...
;             PG8_LDB(B0, 1, 0); PG8_LDB(B1, 1, 1); PG8_SCHED; PG8_LDA(At, 1, 0); PG8_STAGE(PG8_SA(0, 1), a2 + hstep, voffA);
;             PG8_WAIT_V(8); PG8_WAIT_L(0); PG8_BAR; PG8_MMA(0, 0, At, B0); PG8_MMA(0, 1, At, B1); PG8_BAR; PG8_SCHED;
;             PG8_LDA(At, 1, 1); PG8_STAGE(PG8_SB(1, 0), b3, voffB); PG8_STAGE(PG8_SB(1, 1), b3 + hstep, voffB); PG8_STAGE(PG8_SA(1, 0), a3, voffA);
;             PG8_WAIT_V(8); PG8_WAIT_L(0); PG8_BAR; PG8_MMA(1, 0, At, B0); PG8_MMA(1, 1, At, B1); PG8_BAR; PG8_SCHED;
	s_add_i32 s56, 0, 0x18000
	s_add_i32 s57, 0, 0x1c000
	ds_read_b128 v[142:145], v244
	ds_read_b128 v[148:151], v244 offset:1024
	ds_read_b128 v[152:155], v244 offset:2048
	ds_read_b128 v[156:159], v244 offset:3072
	ds_read_b128 v[160:163], v245
	ds_read_b128 v[164:167], v245 offset:1024
	ds_read_b128 v[168:171], v245 offset:2048
	ds_read_b128 v[172:175], v245 offset:3072
	s_add_u32 s22, s22, s4
	s_addc_u32 s23, s23, s5
	s_mov_b32 m0, s35
	ds_read_b128 v[176:179], v147 offset:32768
	ds_read_b128 v[180:183], v147 offset:33792
	ds_read_b128 v[190:193], v147 offset:34816
	ds_read_b128 v[196:199], v147 offset:35840
	ds_read_b128 v[200:203], v147 offset:36864
	ds_read_b128 v[212:215], v147 offset:37888
	ds_read_b128 v[216:219], v147 offset:38912
	ds_read_b128 v[220:223], v147 offset:39936
	global_load_lds_dwordx4 v128, s[22:23]
	s_mov_b32 m0, s36
	s_nop 0
	global_load_lds_dwordx4 v132, s[22:23]
	s_waitcnt vmcnt(8)
	s_waitcnt lgkmcnt(0)
	s_barrier
	s_setprio 1
	s_waitcnt lgkmcnt(0)
	v_mfma_f32_16x16x32_bf16 v[124:127], v[142:145], v[176:179], v[124:127]
	v_mfma_f32_16x16x32_bf16 v[120:123], v[152:155], v[176:179], v[120:123]
	v_mfma_f32_16x16x32_bf16 v[108:111], v[142:145], v[190:193], v[108:111]
	v_mfma_f32_16x16x32_bf16 v[104:107], v[152:155], v[190:193], v[104:107]
	v_mfma_f32_16x16x32_bf16 v[92:95], v[142:145], v[200:203], v[92:95]
	v_mfma_f32_16x16x32_bf16 v[88:91], v[152:155], v[200:203], v[88:91]
	v_mfma_f32_16x16x32_bf16 v[76:79], v[142:145], v[216:219], v[76:79]
	v_mfma_f32_16x16x32_bf16 v[72:75], v[152:155], v[216:219], v[72:75]
	v_mfma_f32_16x16x32_bf16 v[124:127], v[148:151], v[180:183], v[124:127]
	v_mfma_f32_16x16x32_bf16 v[120:123], v[156:159], v[180:183], v[120:123]
	v_mfma_f32_16x16x32_bf16 v[108:111], v[148:151], v[196:199], v[108:111]
	v_mfma_f32_16x16x32_bf16 v[104:107], v[156:159], v[196:199], v[104:107]
	v_mfma_f32_16x16x32_bf16 v[92:95], v[148:151], v[212:215], v[92:95]
	v_mfma_f32_16x16x32_bf16 v[88:91], v[156:159], v[212:215], v[88:91]
	v_mfma_f32_16x16x32_bf16 v[76:79], v[148:151], v[220:223], v[76:79]
	v_mfma_f32_16x16x32_bf16 v[72:75], v[156:159], v[220:223], v[72:75]
	s_setprio 0
	s_setprio 1
	v_mfma_f32_16x16x32_bf16 v[116:119], v[160:163], v[176:179], v[116:119]
	v_mfma_f32_16x16x32_bf16 v[112:115], v[168:171], v[176:179], v[112:115]
	v_mfma_f32_16x16x32_bf16 v[100:103], v[160:163], v[190:193], v[100:103]
	v_mfma_f32_16x16x32_bf16 v[96:99], v[168:171], v[190:193], v[96:99]
	v_mfma_f32_16x16x32_bf16 v[84:87], v[160:163], v[200:203], v[84:87]
	v_mfma_f32_16x16x32_bf16 v[80:83], v[168:171], v[200:203], v[80:83]
	v_mfma_f32_16x16x32_bf16 v[68:71], v[160:163], v[216:219], v[68:71]
	v_mfma_f32_16x16x32_bf16 v[64:67], v[168:171], v[216:219], v[64:67]
	v_mfma_f32_16x16x32_bf16 v[116:119], v[164:167], v[180:183], v[116:119]
	v_mfma_f32_16x16x32_bf16 v[112:115], v[172:175], v[180:183], v[112:115]
	v_mfma_f32_16x16x32_bf16 v[100:103], v[164:167], v[196:199], v[100:103]
	v_mfma_f32_16x16x32_bf16 v[96:99], v[172:175], v[196:199], v[96:99]
	v_mfma_f32_16x16x32_bf16 v[84:87], v[164:167], v[212:215], v[84:87]
	v_mfma_f32_16x16x32_bf16 v[80:83], v[172:175], v[212:215], v[80:83]
	v_mfma_f32_16x16x32_bf16 v[68:71], v[164:167], v[220:223], v[68:71]
	v_mfma_f32_16x16x32_bf16 v[64:67], v[172:175], v[220:223], v[64:67]
	s_setprio 0
	s_barrier
	s_sub_u32 s98, s22, s4
	s_subb_u32 s99, s23, s5
	s_add_u32 s98, s98, 0x80
	s_addc_u32 s99, s99, 0
	s_add_u32 s54, s54, 0x80
	s_addc_u32 s55, s55, 0
	s_sub_u32 s22, s54, s4
	s_subb_u32 s23, s55, s5
	s_add_i32 s56, s56, s30
	s_add_i32 s57, s57, s30
	s_mov_b32 m0, s56
	ds_read_b128 v[176:179], v147 offset:49152
	ds_read_b128 v[180:183], v147 offset:50176
	ds_read_b128 v[190:193], v147 offset:51200
	ds_read_b128 v[196:199], v147 offset:52224
	ds_read_b128 v[200:203], v147 offset:53248
	ds_read_b128 v[212:215], v147 offset:54272
	ds_read_b128 v[216:219], v147 offset:55296
	ds_read_b128 v[220:223], v147 offset:56320
	global_load_lds_dwordx4 v130, s[22:23]
	s_add_i32 m0, s56, 0x2000
	s_nop 0
	global_load_lds_dwordx4 v134, s[22:23]
	s_mov_b32 m0, s57
	s_nop 0
	global_load_lds_dwordx4 v130, s[54:55]
	s_add_i32 m0, s57, 0x2000
	s_nop 0
	global_load_lds_dwordx4 v134, s[54:55]
	s_mov_b32 m0, s38
	s_nop 0
	global_load_lds_dwordx4 v128, s[98:99]
	s_mov_b32 m0, s39
	s_nop 0
	global_load_lds_dwordx4 v132, s[98:99]
	s_waitcnt vmcnt(8)
	s_waitcnt lgkmcnt(0)
	s_barrier
	s_setprio 1
	s_waitcnt lgkmcnt(0)
	v_mfma_f32_16x16x32_bf16 v[60:63], v[142:145], v[176:179], v[60:63]
	v_mfma_f32_16x16x32_bf16 v[56:59], v[152:155], v[176:179], v[56:59]
	v_mfma_f32_16x16x32_bf16 v[44:47], v[142:145], v[190:193], v[44:47]
	v_mfma_f32_16x16x32_bf16 v[40:43], v[152:155], v[190:193], v[40:43]
	v_mfma_f32_16x16x32_bf16 v[28:31], v[142:145], v[200:203], v[28:31]
	v_mfma_f32_16x16x32_bf16 v[24:27], v[152:155], v[200:203], v[24:27]
	v_mfma_f32_16x16x32_bf16 v[12:15], v[142:145], v[216:219], v[12:15]
	v_mfma_f32_16x16x32_bf16 v[8:11], v[152:155], v[216:219], v[8:11]
	v_mfma_f32_16x16x32_bf16 v[60:63], v[148:151], v[180:183], v[60:63]
	v_mfma_f32_16x16x32_bf16 v[56:59], v[156:159], v[180:183], v[56:59]
	v_mfma_f32_16x16x32_bf16 v[44:47], v[148:151], v[196:199], v[44:47]
	v_mfma_f32_16x16x32_bf16 v[40:43], v[156:159], v[196:199], v[40:43]
	v_mfma_f32_16x16x32_bf16 v[28:31], v[148:151], v[212:215], v[28:31]
	v_mfma_f32_16x16x32_bf16 v[24:27], v[156:159], v[212:215], v[24:27]
	v_mfma_f32_16x16x32_bf16 v[12:15], v[148:151], v[220:223], v[12:15]
	v_mfma_f32_16x16x32_bf16 v[8:11], v[156:159], v[220:223], v[8:11]
	s_setprio 0
	s_setprio 1
	v_mfma_f32_16x16x32_bf16 v[52:55], v[160:163], v[176:179], v[52:55]
	v_mfma_f32_16x16x32_bf16 v[48:51], v[168:171], v[176:179], v[48:51]
	v_mfma_f32_16x16x32_bf16 v[36:39], v[160:163], v[190:193], v[36:39]
	v_mfma_f32_16x16x32_bf16 v[32:35], v[168:171], v[190:193], v[32:35]
	v_mfma_f32_16x16x32_bf16 v[20:23], v[160:163], v[200:203], v[20:23]
	v_mfma_f32_16x16x32_bf16 v[16:19], v[168:171], v[200:203], v[16:19]
	v_mfma_f32_16x16x32_bf16 v[4:7], v[160:163], v[216:219], v[4:7]
	v_mfma_f32_16x16x32_bf16 v[0:3], v[168:171], v[216:219], v[0:3]
	v_mfma_f32_16x16x32_bf16 v[52:55], v[164:167], v[180:183], v[52:55]
	v_mfma_f32_16x16x32_bf16 v[48:51], v[172:175], v[180:183], v[48:51]
	v_mfma_f32_16x16x32_bf16 v[36:39], v[164:167], v[196:199], v[36:39]
	v_mfma_f32_16x16x32_bf16 v[32:35], v[172:175], v[196:199], v[32:35]
	v_mfma_f32_16x16x32_bf16 v[20:23], v[164:167], v[212:215], v[20:23]
	v_mfma_f32_16x16x32_bf16 v[16:19], v[172:175], v[212:215], v[16:19]
	v_mfma_f32_16x16x32_bf16 v[4:7], v[164:167], v[220:223], v[4:7]
	v_mfma_f32_16x16x32_bf16 v[0:3], v[172:175], v[220:223], v[0:3]
	s_setprio 0
	s_barrier
	s_add_u32 s20, s20, 0x100
	s_addc_u32 s21, s21, 0
	s_add_u32 s49, s49, 0x100
	s_addc_u32 s50, s50, 0
	s_cmp_ge_i32 s51, s37
	s_mov_b32 s22, s51
	s_cbranch_scc0 .LBB0_237
	v_readlane_b32 s50, v247, 53
	v_readlane_b32 s51, v247, 54
